# v68 + GEMM unit seams: the 128 accumulator registers zeroed with 64 v_mov_b64 instead of 128 v_mov_b32 (15 of the 19 GEMM instances)
# speedup vs baseline: 1.0071x; 1.0051x over previous
.LBB0_125:
	s_ashr_i32 s19, s18, 31
	s_lshl_b64 s[20:21], s[18:19], 19
	s_add_u32 s20, s0, s20
	s_addc_u32 s21, s1, s21
	s_and_b64 s[22:23], s[4:5], exec
	s_cselect_b32 s19, s21, s27
	s_cselect_b32 s45, s20, s26
	s_ashr_i32 s17, s16, 31
	s_lshl_b64 s[22:23], s[16:17], 19
	s_add_u32 s22, s6, s22
	s_addc_u32 s23, s7, s23
	s_and_b64 s[28:29], s[4:5], exec
	s_cselect_b32 s17, s23, s25
	s_cselect_b32 s46, s22, s24
	s_add_u32 s47, s24, 0x100
	s_addc_u32 s48, s25, 0
	s_add_u32 s24, s26, 0x40080
	s_addc_u32 s25, s27, 0
	s_mov_b32 s49, -2
	v_mov_b64_e32 v[0:1], 0
	v_mov_b64_e32 v[2:3], 0
	v_mov_b64_e32 v[4:5], 0
	v_mov_b64_e32 v[6:7], 0
	v_mov_b64_e32 v[8:9], 0
	v_mov_b64_e32 v[10:11], 0
	v_mov_b64_e32 v[12:13], 0
	v_mov_b64_e32 v[14:15], 0
	v_mov_b64_e32 v[16:17], 0
	v_mov_b64_e32 v[18:19], 0
	v_mov_b64_e32 v[20:21], 0
	v_mov_b64_e32 v[22:23], 0
	v_mov_b64_e32 v[24:25], 0
	v_mov_b64_e32 v[26:27], 0
	v_mov_b64_e32 v[28:29], 0
	v_mov_b64_e32 v[30:31], 0
	v_mov_b64_e32 v[32:33], 0
	v_mov_b64_e32 v[34:35], 0
	v_mov_b64_e32 v[36:37], 0
	v_mov_b64_e32 v[38:39], 0
	v_mov_b64_e32 v[40:41], 0
	v_mov_b64_e32 v[42:43], 0
	v_mov_b64_e32 v[44:45], 0
	v_mov_b64_e32 v[46:47], 0
	v_mov_b64_e32 v[48:49], 0
	v_mov_b64_e32 v[50:51], 0
	v_mov_b64_e32 v[52:53], 0
	v_mov_b64_e32 v[54:55], 0
	v_mov_b64_e32 v[56:57], 0
	v_mov_b64_e32 v[58:59], 0
	v_mov_b64_e32 v[60:61], 0
	v_mov_b64_e32 v[62:63], 0
	v_mov_b64_e32 v[64:65], 0
	v_mov_b64_e32 v[66:67], 0
	v_mov_b64_e32 v[68:69], 0
	v_mov_b64_e32 v[70:71], 0
	v_mov_b64_e32 v[72:73], 0
	v_mov_b64_e32 v[74:75], 0
	v_mov_b64_e32 v[76:77], 0
	v_mov_b64_e32 v[78:79], 0
	v_mov_b64_e32 v[80:81], 0
	v_mov_b64_e32 v[82:83], 0
	v_mov_b64_e32 v[84:85], 0
	v_mov_b64_e32 v[86:87], 0
	v_mov_b64_e32 v[88:89], 0
	v_mov_b64_e32 v[90:91], 0
	v_mov_b64_e32 v[92:93], 0
	v_mov_b64_e32 v[94:95], 0
	v_mov_b64_e32 v[96:97], 0
	v_mov_b64_e32 v[98:99], 0
	v_mov_b64_e32 v[100:101], 0
	v_mov_b64_e32 v[102:103], 0
	v_mov_b64_e32 v[104:105], 0
	v_mov_b64_e32 v[106:107], 0
	v_mov_b64_e32 v[108:109], 0
	v_mov_b64_e32 v[110:111], 0
	v_mov_b64_e32 v[112:113], 0
	v_mov_b64_e32 v[114:115], 0
	v_mov_b64_e32 v[116:117], 0
	v_mov_b64_e32 v[118:119], 0
	v_mov_b64_e32 v[120:121], 0
	v_mov_b64_e32 v[122:123], 0
	v_mov_b64_e32 v[124:125], 0
	v_mov_b64_e32 v[126:127], 0

.LBB0_197:
	s_add_u32 s56, s34, 0x100
	s_addc_u32 s57, s35, 0
	s_mov_b32 s58, -2
	v_mov_b64_e32 v[0:1], 0
	v_mov_b64_e32 v[2:3], 0
	v_mov_b64_e32 v[4:5], 0
	v_mov_b64_e32 v[6:7], 0
	v_mov_b64_e32 v[8:9], 0
	v_mov_b64_e32 v[10:11], 0
	v_mov_b64_e32 v[12:13], 0
	v_mov_b64_e32 v[14:15], 0
	v_mov_b64_e32 v[16:17], 0
	v_mov_b64_e32 v[18:19], 0
	v_mov_b64_e32 v[20:21], 0
	v_mov_b64_e32 v[22:23], 0
	v_mov_b64_e32 v[24:25], 0
	v_mov_b64_e32 v[26:27], 0
	v_mov_b64_e32 v[28:29], 0
	v_mov_b64_e32 v[30:31], 0
	v_mov_b64_e32 v[32:33], 0
	v_mov_b64_e32 v[34:35], 0
	v_mov_b64_e32 v[36:37], 0
	v_mov_b64_e32 v[38:39], 0
	v_mov_b64_e32 v[40:41], 0
	v_mov_b64_e32 v[42:43], 0
	v_mov_b64_e32 v[44:45], 0
	v_mov_b64_e32 v[46:47], 0
	v_mov_b64_e32 v[48:49], 0
	v_mov_b64_e32 v[50:51], 0
	v_mov_b64_e32 v[52:53], 0
	v_mov_b64_e32 v[54:55], 0
	v_mov_b64_e32 v[56:57], 0
	v_mov_b64_e32 v[58:59], 0
	v_mov_b64_e32 v[60:61], 0
	v_mov_b64_e32 v[62:63], 0
	v_mov_b64_e32 v[64:65], 0
	v_mov_b64_e32 v[66:67], 0
	v_mov_b64_e32 v[68:69], 0
	v_mov_b64_e32 v[70:71], 0
	v_mov_b64_e32 v[72:73], 0
	v_mov_b64_e32 v[74:75], 0
	v_mov_b64_e32 v[76:77], 0
	v_mov_b64_e32 v[78:79], 0
	v_mov_b64_e32 v[80:81], 0
	v_mov_b64_e32 v[82:83], 0
	v_mov_b64_e32 v[84:85], 0
	v_mov_b64_e32 v[86:87], 0
	v_mov_b64_e32 v[88:89], 0
	v_mov_b64_e32 v[90:91], 0
	v_mov_b64_e32 v[92:93], 0
	v_mov_b64_e32 v[94:95], 0
	v_mov_b64_e32 v[96:97], 0
	v_mov_b64_e32 v[98:99], 0
	v_mov_b64_e32 v[100:101], 0
	v_mov_b64_e32 v[102:103], 0
	v_mov_b64_e32 v[104:105], 0
	v_mov_b64_e32 v[106:107], 0
	v_mov_b64_e32 v[108:109], 0
	v_mov_b64_e32 v[110:111], 0
	v_mov_b64_e32 v[112:113], 0
	v_mov_b64_e32 v[114:115], 0
	v_mov_b64_e32 v[116:117], 0
	v_mov_b64_e32 v[118:119], 0
	v_mov_b64_e32 v[120:121], 0
	v_mov_b64_e32 v[122:123], 0
	v_mov_b64_e32 v[124:125], 0
	v_mov_b64_e32 v[126:127], 0

.LBB0_355:
	s_ashr_i32 s19, s18, 31
	s_lshl_b64 s[20:21], s[18:19], 19
	s_add_u32 s20, s0, s20
	s_addc_u32 s21, s1, s21
	s_and_b64 s[22:23], s[4:5], exec
	s_cselect_b32 s19, s21, s29
	s_cselect_b32 s45, s20, s28
	s_ashr_i32 s17, s16, 31
	s_lshl_b64 s[22:23], s[16:17], 19
	s_add_u32 s22, s6, s22
	s_addc_u32 s23, s7, s23
	s_and_b64 s[30:31], s[4:5], exec
	s_cselect_b32 s17, s23, s27
	s_cselect_b32 s46, s22, s26
	s_add_u32 s47, s26, 0x100
	s_addc_u32 s48, s27, 0
	s_add_u32 s26, s28, 0x40080
	s_addc_u32 s27, s29, 0
	s_mov_b32 s49, -2
	v_mov_b64_e32 v[0:1], 0
	v_mov_b64_e32 v[2:3], 0
	v_mov_b64_e32 v[4:5], 0
	v_mov_b64_e32 v[6:7], 0
	v_mov_b64_e32 v[8:9], 0
	v_mov_b64_e32 v[10:11], 0
	v_mov_b64_e32 v[12:13], 0
	v_mov_b64_e32 v[14:15], 0
	v_mov_b64_e32 v[16:17], 0
	v_mov_b64_e32 v[18:19], 0
	v_mov_b64_e32 v[20:21], 0
	v_mov_b64_e32 v[22:23], 0
	v_mov_b64_e32 v[24:25], 0
	v_mov_b64_e32 v[26:27], 0
	v_mov_b64_e32 v[28:29], 0
	v_mov_b64_e32 v[30:31], 0
	v_mov_b64_e32 v[32:33], 0
	v_mov_b64_e32 v[34:35], 0
	v_mov_b64_e32 v[36:37], 0
	v_mov_b64_e32 v[38:39], 0
	v_mov_b64_e32 v[40:41], 0
	v_mov_b64_e32 v[42:43], 0
	v_mov_b64_e32 v[44:45], 0
	v_mov_b64_e32 v[46:47], 0
	v_mov_b64_e32 v[48:49], 0
	v_mov_b64_e32 v[50:51], 0
	v_mov_b64_e32 v[52:53], 0
	v_mov_b64_e32 v[54:55], 0
	v_mov_b64_e32 v[56:57], 0
	v_mov_b64_e32 v[58:59], 0
	v_mov_b64_e32 v[60:61], 0
	v_mov_b64_e32 v[62:63], 0
	v_mov_b64_e32 v[64:65], 0
	v_mov_b64_e32 v[66:67], 0
	v_mov_b64_e32 v[68:69], 0
	v_mov_b64_e32 v[70:71], 0
	v_mov_b64_e32 v[72:73], 0
	v_mov_b64_e32 v[74:75], 0
	v_mov_b64_e32 v[76:77], 0
	v_mov_b64_e32 v[78:79], 0
	v_mov_b64_e32 v[80:81], 0
	v_mov_b64_e32 v[82:83], 0
	v_mov_b64_e32 v[84:85], 0
	v_mov_b64_e32 v[86:87], 0
	v_mov_b64_e32 v[88:89], 0
	v_mov_b64_e32 v[90:91], 0
	v_mov_b64_e32 v[92:93], 0
	v_mov_b64_e32 v[94:95], 0
	v_mov_b64_e32 v[96:97], 0
	v_mov_b64_e32 v[98:99], 0
	v_mov_b64_e32 v[100:101], 0
	v_mov_b64_e32 v[102:103], 0
	v_mov_b64_e32 v[104:105], 0
	v_mov_b64_e32 v[106:107], 0
	v_mov_b64_e32 v[108:109], 0
	v_mov_b64_e32 v[110:111], 0
	v_mov_b64_e32 v[112:113], 0
	v_mov_b64_e32 v[114:115], 0
	v_mov_b64_e32 v[116:117], 0
	v_mov_b64_e32 v[118:119], 0
	v_mov_b64_e32 v[120:121], 0
	v_mov_b64_e32 v[122:123], 0
	v_mov_b64_e32 v[124:125], 0
	v_mov_b64_e32 v[126:127], 0

.LBB0_728:
	s_ashr_i32 s27, s26, 31
	s_lshl_b64 s[28:29], s[26:27], 19
	s_add_u32 s28, s8, s28
	s_addc_u32 s29, s9, s29
	s_and_b64 s[30:31], s[6:7], exec
	s_cselect_b32 s27, s29, s37
	s_cselect_b32 s55, s28, s36
	s_ashr_i32 s25, s24, 31
	s_lshl_b64 s[30:31], s[24:25], 19
	s_add_u32 s30, s0, s30
	s_addc_u32 s31, s1, s31
	s_and_b64 s[38:39], s[6:7], exec
	s_cselect_b32 s25, s31, s35
	s_cselect_b32 s56, s30, s34
	s_add_u32 s57, s34, 0x100
	s_addc_u32 s58, s35, 0
	s_add_u32 s34, s36, 0x40080
	s_addc_u32 s35, s37, 0
	s_mov_b32 s59, -2
	v_mov_b64_e32 v[0:1], 0
	v_mov_b64_e32 v[2:3], 0
	v_mov_b64_e32 v[4:5], 0
	v_mov_b64_e32 v[6:7], 0
	v_mov_b64_e32 v[8:9], 0
	v_mov_b64_e32 v[10:11], 0
	v_mov_b64_e32 v[12:13], 0
	v_mov_b64_e32 v[14:15], 0
	v_mov_b64_e32 v[16:17], 0
	v_mov_b64_e32 v[18:19], 0
	v_mov_b64_e32 v[20:21], 0
	v_mov_b64_e32 v[22:23], 0
	v_mov_b64_e32 v[24:25], 0
	v_mov_b64_e32 v[26:27], 0
	v_mov_b64_e32 v[28:29], 0
	v_mov_b64_e32 v[30:31], 0
	v_mov_b64_e32 v[32:33], 0
	v_mov_b64_e32 v[34:35], 0
	v_mov_b64_e32 v[36:37], 0
	v_mov_b64_e32 v[38:39], 0
	v_mov_b64_e32 v[40:41], 0
	v_mov_b64_e32 v[42:43], 0
	v_mov_b64_e32 v[44:45], 0
	v_mov_b64_e32 v[46:47], 0
	v_mov_b64_e32 v[48:49], 0
	v_mov_b64_e32 v[50:51], 0
	v_mov_b64_e32 v[52:53], 0
	v_mov_b64_e32 v[54:55], 0
	v_mov_b64_e32 v[56:57], 0
	v_mov_b64_e32 v[58:59], 0
	v_mov_b64_e32 v[60:61], 0
	v_mov_b64_e32 v[62:63], 0
	v_mov_b64_e32 v[64:65], 0
	v_mov_b64_e32 v[66:67], 0
	v_mov_b64_e32 v[68:69], 0
	v_mov_b64_e32 v[70:71], 0
	v_mov_b64_e32 v[72:73], 0
	v_mov_b64_e32 v[74:75], 0
	v_mov_b64_e32 v[76:77], 0
	v_mov_b64_e32 v[78:79], 0
	v_mov_b64_e32 v[80:81], 0
	v_mov_b64_e32 v[82:83], 0
	v_mov_b64_e32 v[84:85], 0
	v_mov_b64_e32 v[86:87], 0
	v_mov_b64_e32 v[88:89], 0
	v_mov_b64_e32 v[90:91], 0
	v_mov_b64_e32 v[92:93], 0
	v_mov_b64_e32 v[94:95], 0
	v_mov_b64_e32 v[96:97], 0
	v_mov_b64_e32 v[98:99], 0
	v_mov_b64_e32 v[100:101], 0
	v_mov_b64_e32 v[102:103], 0
	v_mov_b64_e32 v[104:105], 0
	v_mov_b64_e32 v[106:107], 0
	v_mov_b64_e32 v[108:109], 0
	v_mov_b64_e32 v[110:111], 0
	v_mov_b64_e32 v[112:113], 0
	v_mov_b64_e32 v[114:115], 0
	v_mov_b64_e32 v[116:117], 0
	v_mov_b64_e32 v[118:119], 0
	v_mov_b64_e32 v[120:121], 0
	v_mov_b64_e32 v[122:123], 0
	v_mov_b64_e32 v[124:125], 0
	v_mov_b64_e32 v[126:127], 0

.LBB0_876:
	s_ashr_i32 s19, s18, 31
	s_lshl_b64 s[20:21], s[18:19], 19
	s_add_u32 s20, s0, s20
	s_addc_u32 s21, s1, s21
	s_and_b64 s[22:23], s[6:7], exec
	s_cselect_b32 s19, s21, s27
	s_cselect_b32 s45, s20, s26
	s_ashr_i32 s17, s16, 31
	s_lshl_b64 s[22:23], s[16:17], 19
	s_add_u32 s22, s4, s22
	s_addc_u32 s23, s5, s23
	s_and_b64 s[28:29], s[6:7], exec
	s_cselect_b32 s17, s23, s25
	s_cselect_b32 s46, s22, s24
	s_add_u32 s47, s24, 0x100
	s_addc_u32 s48, s25, 0
	s_add_u32 s24, s26, 0x40080
	s_addc_u32 s25, s27, 0
	s_mov_b32 s49, -2
	v_mov_b64_e32 v[0:1], 0
	v_mov_b64_e32 v[2:3], 0
	v_mov_b64_e32 v[4:5], 0
	v_mov_b64_e32 v[6:7], 0
	v_mov_b64_e32 v[8:9], 0
	v_mov_b64_e32 v[10:11], 0
	v_mov_b64_e32 v[12:13], 0
	v_mov_b64_e32 v[14:15], 0
	v_mov_b64_e32 v[16:17], 0
	v_mov_b64_e32 v[18:19], 0
	v_mov_b64_e32 v[20:21], 0
	v_mov_b64_e32 v[22:23], 0
	v_mov_b64_e32 v[24:25], 0
	v_mov_b64_e32 v[26:27], 0
	v_mov_b64_e32 v[28:29], 0
	v_mov_b64_e32 v[30:31], 0
	v_mov_b64_e32 v[32:33], 0
	v_mov_b64_e32 v[34:35], 0
	v_mov_b64_e32 v[36:37], 0
	v_mov_b64_e32 v[38:39], 0
	v_mov_b64_e32 v[40:41], 0
	v_mov_b64_e32 v[42:43], 0
	v_mov_b64_e32 v[44:45], 0
	v_mov_b64_e32 v[46:47], 0
	v_mov_b64_e32 v[48:49], 0
	v_mov_b64_e32 v[50:51], 0
	v_mov_b64_e32 v[52:53], 0
	v_mov_b64_e32 v[54:55], 0
	v_mov_b64_e32 v[56:57], 0
	v_mov_b64_e32 v[58:59], 0
	v_mov_b64_e32 v[60:61], 0
	v_mov_b64_e32 v[62:63], 0
	v_mov_b64_e32 v[64:65], 0
	v_mov_b64_e32 v[66:67], 0
	v_mov_b64_e32 v[68:69], 0
	v_mov_b64_e32 v[70:71], 0
	v_mov_b64_e32 v[72:73], 0
	v_mov_b64_e32 v[74:75], 0
	v_mov_b64_e32 v[76:77], 0
	v_mov_b64_e32 v[78:79], 0
	v_mov_b64_e32 v[80:81], 0
	v_mov_b64_e32 v[82:83], 0
	v_mov_b64_e32 v[84:85], 0
	v_mov_b64_e32 v[86:87], 0
	v_mov_b64_e32 v[88:89], 0
	v_mov_b64_e32 v[90:91], 0
	v_mov_b64_e32 v[92:93], 0
	v_mov_b64_e32 v[94:95], 0
	v_mov_b64_e32 v[96:97], 0
	v_mov_b64_e32 v[98:99], 0
	v_mov_b64_e32 v[100:101], 0
	v_mov_b64_e32 v[102:103], 0
	v_mov_b64_e32 v[104:105], 0
	v_mov_b64_e32 v[106:107], 0
	v_mov_b64_e32 v[108:109], 0
	v_mov_b64_e32 v[110:111], 0
	v_mov_b64_e32 v[112:113], 0
	v_mov_b64_e32 v[114:115], 0
	v_mov_b64_e32 v[116:117], 0
	v_mov_b64_e32 v[118:119], 0
	v_mov_b64_e32 v[120:121], 0
	v_mov_b64_e32 v[122:123], 0
	v_mov_b64_e32 v[124:125], 0
	v_mov_b64_e32 v[126:127], 0

.LBB0_948:
	s_add_u32 s57, s34, 0x100
	s_addc_u32 s58, s35, 0
	s_mov_b32 s59, -2
	v_mov_b64_e32 v[0:1], 0
	v_mov_b64_e32 v[2:3], 0
	v_mov_b64_e32 v[4:5], 0
	v_mov_b64_e32 v[6:7], 0
	v_mov_b64_e32 v[8:9], 0
	v_mov_b64_e32 v[10:11], 0
	v_mov_b64_e32 v[12:13], 0
	v_mov_b64_e32 v[14:15], 0
	v_mov_b64_e32 v[16:17], 0
	v_mov_b64_e32 v[18:19], 0
	v_mov_b64_e32 v[20:21], 0
	v_mov_b64_e32 v[22:23], 0
	v_mov_b64_e32 v[24:25], 0
	v_mov_b64_e32 v[26:27], 0
	v_mov_b64_e32 v[28:29], 0
	v_mov_b64_e32 v[30:31], 0
	v_mov_b64_e32 v[32:33], 0
	v_mov_b64_e32 v[34:35], 0
	v_mov_b64_e32 v[36:37], 0
	v_mov_b64_e32 v[38:39], 0
	v_mov_b64_e32 v[40:41], 0
	v_mov_b64_e32 v[42:43], 0
	v_mov_b64_e32 v[44:45], 0
	v_mov_b64_e32 v[46:47], 0
	v_mov_b64_e32 v[48:49], 0
	v_mov_b64_e32 v[50:51], 0
	v_mov_b64_e32 v[52:53], 0
	v_mov_b64_e32 v[54:55], 0
	v_mov_b64_e32 v[56:57], 0
	v_mov_b64_e32 v[58:59], 0
	v_mov_b64_e32 v[60:61], 0
	v_mov_b64_e32 v[62:63], 0
	v_mov_b64_e32 v[64:65], 0
	v_mov_b64_e32 v[66:67], 0
	v_mov_b64_e32 v[68:69], 0
	v_mov_b64_e32 v[70:71], 0
	v_mov_b64_e32 v[72:73], 0
	v_mov_b64_e32 v[74:75], 0
	v_mov_b64_e32 v[76:77], 0
	v_mov_b64_e32 v[78:79], 0
	v_mov_b64_e32 v[80:81], 0
	v_mov_b64_e32 v[82:83], 0
	v_mov_b64_e32 v[84:85], 0
	v_mov_b64_e32 v[86:87], 0
	v_mov_b64_e32 v[88:89], 0
	v_mov_b64_e32 v[90:91], 0
	v_mov_b64_e32 v[92:93], 0
	v_mov_b64_e32 v[94:95], 0
	v_mov_b64_e32 v[96:97], 0
	v_mov_b64_e32 v[98:99], 0
	v_mov_b64_e32 v[100:101], 0
	v_mov_b64_e32 v[102:103], 0
	v_mov_b64_e32 v[104:105], 0
	v_mov_b64_e32 v[106:107], 0
	v_mov_b64_e32 v[108:109], 0
	v_mov_b64_e32 v[110:111], 0
	v_mov_b64_e32 v[112:113], 0
	v_mov_b64_e32 v[114:115], 0
	v_mov_b64_e32 v[116:117], 0
	v_mov_b64_e32 v[118:119], 0
	v_mov_b64_e32 v[120:121], 0
	v_mov_b64_e32 v[122:123], 0
	v_mov_b64_e32 v[124:125], 0
	v_mov_b64_e32 v[126:127], 0

.LBB0_1110:
	s_ashr_i32 s31, s30, 31
	s_lshl_b64 s[34:35], s[30:31], 19
	s_add_u32 s34, s10, s34
	s_addc_u32 s35, s11, s35
	s_and_b64 s[36:37], s[8:9], exec
	s_cselect_b32 s31, s35, s43
	s_cselect_b32 s59, s34, s42
	s_ashr_i32 s29, s28, 31
	s_lshl_b64 s[36:37], s[28:29], 19
	s_add_u32 s36, s12, s36
	s_addc_u32 s37, s13, s37
	s_and_b64 s[44:45], s[8:9], exec
	s_cselect_b32 s29, s37, s41
	s_cselect_b32 s60, s36, s40
	s_add_u32 s61, s40, 0x100
	s_addc_u32 s62, s41, 0
	s_add_u32 s40, s42, 0x40080
	s_addc_u32 s41, s43, 0
	s_mov_b32 s63, -2
	v_mov_b64_e32 v[0:1], 0
	v_mov_b64_e32 v[2:3], 0
	v_mov_b64_e32 v[4:5], 0
	v_mov_b64_e32 v[6:7], 0
	v_mov_b64_e32 v[8:9], 0
	v_mov_b64_e32 v[10:11], 0
	v_mov_b64_e32 v[12:13], 0
	v_mov_b64_e32 v[14:15], 0
	v_mov_b64_e32 v[16:17], 0
	v_mov_b64_e32 v[18:19], 0
	v_mov_b64_e32 v[20:21], 0
	v_mov_b64_e32 v[22:23], 0
	v_mov_b64_e32 v[24:25], 0
	v_mov_b64_e32 v[26:27], 0
	v_mov_b64_e32 v[28:29], 0
	v_mov_b64_e32 v[30:31], 0
	v_mov_b64_e32 v[32:33], 0
	v_mov_b64_e32 v[34:35], 0
	v_mov_b64_e32 v[36:37], 0
	v_mov_b64_e32 v[38:39], 0
	v_mov_b64_e32 v[40:41], 0
	v_mov_b64_e32 v[42:43], 0
	v_mov_b64_e32 v[44:45], 0
	v_mov_b64_e32 v[46:47], 0
	v_mov_b64_e32 v[48:49], 0
	v_mov_b64_e32 v[50:51], 0
	v_mov_b64_e32 v[52:53], 0
	v_mov_b64_e32 v[54:55], 0
	v_mov_b64_e32 v[56:57], 0
	v_mov_b64_e32 v[58:59], 0
	v_mov_b64_e32 v[60:61], 0
	v_mov_b64_e32 v[62:63], 0
	v_mov_b64_e32 v[64:65], 0
	v_mov_b64_e32 v[66:67], 0
	v_mov_b64_e32 v[68:69], 0
	v_mov_b64_e32 v[70:71], 0
	v_mov_b64_e32 v[72:73], 0
	v_mov_b64_e32 v[74:75], 0
	v_mov_b64_e32 v[76:77], 0
	v_mov_b64_e32 v[78:79], 0
	v_mov_b64_e32 v[80:81], 0
	v_mov_b64_e32 v[82:83], 0
	v_mov_b64_e32 v[84:85], 0
	v_mov_b64_e32 v[86:87], 0
	v_mov_b64_e32 v[88:89], 0
	v_mov_b64_e32 v[90:91], 0
	v_mov_b64_e32 v[92:93], 0
	v_mov_b64_e32 v[94:95], 0
	v_mov_b64_e32 v[96:97], 0
	v_mov_b64_e32 v[98:99], 0
	v_mov_b64_e32 v[100:101], 0
	v_mov_b64_e32 v[102:103], 0
	v_mov_b64_e32 v[104:105], 0
	v_mov_b64_e32 v[106:107], 0
	v_mov_b64_e32 v[108:109], 0
	v_mov_b64_e32 v[110:111], 0
	v_mov_b64_e32 v[112:113], 0
	v_mov_b64_e32 v[114:115], 0
	v_mov_b64_e32 v[116:117], 0
	v_mov_b64_e32 v[118:119], 0
	v_mov_b64_e32 v[120:121], 0
	v_mov_b64_e32 v[122:123], 0
	v_mov_b64_e32 v[124:125], 0
	v_mov_b64_e32 v[126:127], 0

.LBB0_1280:
	s_ashr_i32 s21, s20, 31
	s_lshl_b64 s[22:23], s[20:21], 19
	s_add_u32 s22, s0, s22
	s_addc_u32 s23, s1, s23
	s_and_b64 s[24:25], s[8:9], exec
	s_cselect_b32 s21, s23, s29
	s_cselect_b32 s47, s22, s28
	s_ashr_i32 s19, s18, 31
	s_lshl_b64 s[24:25], s[18:19], 19
	s_add_u32 s24, s4, s24
	s_addc_u32 s25, s5, s25
	s_and_b64 s[30:31], s[8:9], exec
	s_cselect_b32 s19, s25, s27
	s_cselect_b32 s48, s24, s26
	s_add_u32 s49, s26, 0x100
	s_addc_u32 s50, s27, 0
	s_add_u32 s26, s28, 0x40080
	s_addc_u32 s27, s29, 0
	s_mov_b32 s51, -2
	v_mov_b64_e32 v[0:1], 0
	v_mov_b64_e32 v[2:3], 0
	v_mov_b64_e32 v[4:5], 0
	v_mov_b64_e32 v[6:7], 0
	v_mov_b64_e32 v[8:9], 0
	v_mov_b64_e32 v[10:11], 0
	v_mov_b64_e32 v[12:13], 0
	v_mov_b64_e32 v[14:15], 0
	v_mov_b64_e32 v[16:17], 0
	v_mov_b64_e32 v[18:19], 0
	v_mov_b64_e32 v[20:21], 0
	v_mov_b64_e32 v[22:23], 0
	v_mov_b64_e32 v[24:25], 0
	v_mov_b64_e32 v[26:27], 0
	v_mov_b64_e32 v[28:29], 0
	v_mov_b64_e32 v[30:31], 0
	v_mov_b64_e32 v[32:33], 0
	v_mov_b64_e32 v[34:35], 0
	v_mov_b64_e32 v[36:37], 0
	v_mov_b64_e32 v[38:39], 0
	v_mov_b64_e32 v[40:41], 0
	v_mov_b64_e32 v[42:43], 0
	v_mov_b64_e32 v[44:45], 0
	v_mov_b64_e32 v[46:47], 0
	v_mov_b64_e32 v[48:49], 0
	v_mov_b64_e32 v[50:51], 0
	v_mov_b64_e32 v[52:53], 0
	v_mov_b64_e32 v[54:55], 0
	v_mov_b64_e32 v[56:57], 0
	v_mov_b64_e32 v[58:59], 0
	v_mov_b64_e32 v[60:61], 0
	v_mov_b64_e32 v[62:63], 0
	v_mov_b64_e32 v[64:65], 0
	v_mov_b64_e32 v[66:67], 0
	v_mov_b64_e32 v[68:69], 0
	v_mov_b64_e32 v[70:71], 0
	v_mov_b64_e32 v[72:73], 0
	v_mov_b64_e32 v[74:75], 0
	v_mov_b64_e32 v[76:77], 0
	v_mov_b64_e32 v[78:79], 0
	v_mov_b64_e32 v[80:81], 0
	v_mov_b64_e32 v[82:83], 0
	v_mov_b64_e32 v[84:85], 0
	v_mov_b64_e32 v[86:87], 0
	v_mov_b64_e32 v[88:89], 0
	v_mov_b64_e32 v[90:91], 0
	v_mov_b64_e32 v[92:93], 0
	v_mov_b64_e32 v[94:95], 0
	v_mov_b64_e32 v[96:97], 0
	v_mov_b64_e32 v[98:99], 0
	v_mov_b64_e32 v[100:101], 0
	v_mov_b64_e32 v[102:103], 0
	v_mov_b64_e32 v[104:105], 0
	v_mov_b64_e32 v[106:107], 0
	v_mov_b64_e32 v[108:109], 0
	v_mov_b64_e32 v[110:111], 0
	v_mov_b64_e32 v[112:113], 0
	v_mov_b64_e32 v[114:115], 0
	v_mov_b64_e32 v[116:117], 0
	v_mov_b64_e32 v[118:119], 0
	v_mov_b64_e32 v[120:121], 0
	v_mov_b64_e32 v[122:123], 0
	v_mov_b64_e32 v[124:125], 0
	v_mov_b64_e32 v[126:127], 0

.LBB0_1512:
	s_ashr_i32 s31, s30, 31
	s_lshl_b64 s[34:35], s[30:31], 19
	s_add_u32 s34, s4, s34
	s_addc_u32 s35, s5, s35
	s_and_b64 s[36:37], s[8:9], exec
	s_cselect_b32 s31, s35, s41
	s_cselect_b32 s59, s34, s40
	s_ashr_i32 s29, s28, 31
	s_lshl_b64 s[36:37], s[28:29], 19
	s_add_u32 s36, s10, s36
	s_addc_u32 s37, s11, s37
	s_and_b64 s[42:43], s[8:9], exec
	s_cselect_b32 s29, s37, s39
	s_cselect_b32 s60, s36, s38
	s_add_u32 s61, s38, 0x100
	s_addc_u32 s62, s39, 0
	s_add_u32 s38, s40, 0x40080
	s_addc_u32 s39, s41, 0
	s_mov_b32 s63, -2
	v_mov_b64_e32 v[0:1], 0
	v_mov_b64_e32 v[2:3], 0
	v_mov_b64_e32 v[4:5], 0
	v_mov_b64_e32 v[6:7], 0
	v_mov_b64_e32 v[8:9], 0
	v_mov_b64_e32 v[10:11], 0
	v_mov_b64_e32 v[12:13], 0
	v_mov_b64_e32 v[14:15], 0
	v_mov_b64_e32 v[16:17], 0
	v_mov_b64_e32 v[18:19], 0
	v_mov_b64_e32 v[20:21], 0
	v_mov_b64_e32 v[22:23], 0
	v_mov_b64_e32 v[24:25], 0
	v_mov_b64_e32 v[26:27], 0
	v_mov_b64_e32 v[28:29], 0
	v_mov_b64_e32 v[30:31], 0
	v_mov_b64_e32 v[32:33], 0
	v_mov_b64_e32 v[34:35], 0
	v_mov_b64_e32 v[36:37], 0
	v_mov_b64_e32 v[38:39], 0
	v_mov_b64_e32 v[40:41], 0
	v_mov_b64_e32 v[42:43], 0
	v_mov_b64_e32 v[44:45], 0
	v_mov_b64_e32 v[46:47], 0
	v_mov_b64_e32 v[48:49], 0
	v_mov_b64_e32 v[50:51], 0
	v_mov_b64_e32 v[52:53], 0
	v_mov_b64_e32 v[54:55], 0
	v_mov_b64_e32 v[56:57], 0
	v_mov_b64_e32 v[58:59], 0
	v_mov_b64_e32 v[60:61], 0
	v_mov_b64_e32 v[62:63], 0
	v_mov_b64_e32 v[64:65], 0
	v_mov_b64_e32 v[66:67], 0
	v_mov_b64_e32 v[68:69], 0
	v_mov_b64_e32 v[70:71], 0
	v_mov_b64_e32 v[72:73], 0
	v_mov_b64_e32 v[74:75], 0
	v_mov_b64_e32 v[76:77], 0
	v_mov_b64_e32 v[78:79], 0
	v_mov_b64_e32 v[80:81], 0
	v_mov_b64_e32 v[82:83], 0
	v_mov_b64_e32 v[84:85], 0
	v_mov_b64_e32 v[86:87], 0
	v_mov_b64_e32 v[88:89], 0
	v_mov_b64_e32 v[90:91], 0
	v_mov_b64_e32 v[92:93], 0
	v_mov_b64_e32 v[94:95], 0
	v_mov_b64_e32 v[96:97], 0
	v_mov_b64_e32 v[98:99], 0
	v_mov_b64_e32 v[100:101], 0
	v_mov_b64_e32 v[102:103], 0
	v_mov_b64_e32 v[104:105], 0
	v_mov_b64_e32 v[106:107], 0
	v_mov_b64_e32 v[108:109], 0
	v_mov_b64_e32 v[110:111], 0
	v_mov_b64_e32 v[112:113], 0
	v_mov_b64_e32 v[114:115], 0
	v_mov_b64_e32 v[116:117], 0
	v_mov_b64_e32 v[118:119], 0
	v_mov_b64_e32 v[120:121], 0
	v_mov_b64_e32 v[122:123], 0
	v_mov_b64_e32 v[124:125], 0
	v_mov_b64_e32 v[126:127], 0

.LBB0_1528:
	s_ashr_i32 s31, s30, 31
	s_lshl_b64 s[34:35], s[30:31], 19
	s_add_u32 s34, s4, s34
	s_addc_u32 s35, s5, s35
	s_and_b64 s[36:37], s[8:9], exec
	s_cselect_b32 s31, s35, s41
	s_cselect_b32 s58, s34, s40
	s_ashr_i32 s29, s28, 31
	s_lshl_b64 s[36:37], s[28:29], 19
	s_add_u32 s36, s10, s36
	s_addc_u32 s37, s11, s37
	s_and_b64 s[42:43], s[8:9], exec
	s_cselect_b32 s29, s37, s39
	s_cselect_b32 s59, s36, s38
	s_add_u32 s60, s38, 0x100
	s_addc_u32 s61, s39, 0
	s_add_u32 s38, s40, 0x40080
	s_addc_u32 s39, s41, 0
	s_mov_b32 s62, -2
	v_mov_b64_e32 v[0:1], 0
	v_mov_b64_e32 v[2:3], 0
	v_mov_b64_e32 v[4:5], 0
	v_mov_b64_e32 v[6:7], 0
	v_mov_b64_e32 v[8:9], 0
	v_mov_b64_e32 v[10:11], 0
	v_mov_b64_e32 v[12:13], 0
	v_mov_b64_e32 v[14:15], 0
	v_mov_b64_e32 v[16:17], 0
	v_mov_b64_e32 v[18:19], 0
	v_mov_b64_e32 v[20:21], 0
	v_mov_b64_e32 v[22:23], 0
	v_mov_b64_e32 v[24:25], 0
	v_mov_b64_e32 v[26:27], 0
	v_mov_b64_e32 v[28:29], 0
	v_mov_b64_e32 v[30:31], 0
	v_mov_b64_e32 v[32:33], 0
	v_mov_b64_e32 v[34:35], 0
	v_mov_b64_e32 v[36:37], 0
	v_mov_b64_e32 v[38:39], 0
	v_mov_b64_e32 v[40:41], 0
	v_mov_b64_e32 v[42:43], 0
	v_mov_b64_e32 v[44:45], 0
	v_mov_b64_e32 v[46:47], 0
	v_mov_b64_e32 v[48:49], 0
	v_mov_b64_e32 v[50:51], 0
	v_mov_b64_e32 v[52:53], 0
	v_mov_b64_e32 v[54:55], 0
	v_mov_b64_e32 v[56:57], 0
	v_mov_b64_e32 v[58:59], 0
	v_mov_b64_e32 v[60:61], 0
	v_mov_b64_e32 v[62:63], 0
	v_mov_b64_e32 v[64:65], 0
	v_mov_b64_e32 v[66:67], 0
	v_mov_b64_e32 v[68:69], 0
	v_mov_b64_e32 v[70:71], 0
	v_mov_b64_e32 v[72:73], 0
	v_mov_b64_e32 v[74:75], 0
	v_mov_b64_e32 v[76:77], 0
	v_mov_b64_e32 v[78:79], 0
	v_mov_b64_e32 v[80:81], 0
	v_mov_b64_e32 v[82:83], 0
	v_mov_b64_e32 v[84:85], 0
	v_mov_b64_e32 v[86:87], 0
	v_mov_b64_e32 v[88:89], 0
	v_mov_b64_e32 v[90:91], 0
	v_mov_b64_e32 v[92:93], 0
	v_mov_b64_e32 v[94:95], 0
	v_mov_b64_e32 v[96:97], 0
	v_mov_b64_e32 v[98:99], 0
	v_mov_b64_e32 v[100:101], 0
	v_mov_b64_e32 v[102:103], 0
	v_mov_b64_e32 v[104:105], 0
	v_mov_b64_e32 v[106:107], 0
	v_mov_b64_e32 v[108:109], 0
	v_mov_b64_e32 v[110:111], 0
	v_mov_b64_e32 v[112:113], 0
	v_mov_b64_e32 v[114:115], 0
	v_mov_b64_e32 v[116:117], 0
	v_mov_b64_e32 v[118:119], 0
	v_mov_b64_e32 v[120:121], 0
	v_mov_b64_e32 v[122:123], 0
	v_mov_b64_e32 v[124:125], 0
	v_mov_b64_e32 v[126:127], 0

.LBB0_1800:
	s_ashr_i32 s29, s28, 31
	s_lshl_b64 s[30:31], s[28:29], 19
	s_add_u32 s30, s0, s30
	s_addc_u32 s31, s1, s31
	s_and_b64 s[34:35], s[8:9], exec
	s_cselect_b32 s29, s31, s39
	s_cselect_b32 s57, s30, s38
	s_ashr_i32 s27, s26, 31
	s_lshl_b64 s[34:35], s[26:27], 19
	s_add_u32 s34, s4, s34
	s_addc_u32 s35, s5, s35
	s_and_b64 s[40:41], s[8:9], exec
	s_cselect_b32 s27, s35, s37
	s_cselect_b32 s58, s34, s36
	s_add_u32 s59, s36, 0x100
	s_addc_u32 s60, s37, 0
	s_add_u32 s36, s38, 0x40080
	s_addc_u32 s37, s39, 0
	s_mov_b32 s61, -2
	v_mov_b64_e32 v[0:1], 0
	v_mov_b64_e32 v[2:3], 0
	v_mov_b64_e32 v[4:5], 0
	v_mov_b64_e32 v[6:7], 0
	v_mov_b64_e32 v[8:9], 0
	v_mov_b64_e32 v[10:11], 0
	v_mov_b64_e32 v[12:13], 0
	v_mov_b64_e32 v[14:15], 0
	v_mov_b64_e32 v[16:17], 0
	v_mov_b64_e32 v[18:19], 0
	v_mov_b64_e32 v[20:21], 0
	v_mov_b64_e32 v[22:23], 0
	v_mov_b64_e32 v[24:25], 0
	v_mov_b64_e32 v[26:27], 0
	v_mov_b64_e32 v[28:29], 0
	v_mov_b64_e32 v[30:31], 0
	v_mov_b64_e32 v[32:33], 0
	v_mov_b64_e32 v[34:35], 0
	v_mov_b64_e32 v[36:37], 0
	v_mov_b64_e32 v[38:39], 0
	v_mov_b64_e32 v[40:41], 0
	v_mov_b64_e32 v[42:43], 0
	v_mov_b64_e32 v[44:45], 0
	v_mov_b64_e32 v[46:47], 0
	v_mov_b64_e32 v[48:49], 0
	v_mov_b64_e32 v[50:51], 0
	v_mov_b64_e32 v[52:53], 0
	v_mov_b64_e32 v[54:55], 0
	v_mov_b64_e32 v[56:57], 0
	v_mov_b64_e32 v[58:59], 0
	v_mov_b64_e32 v[60:61], 0
	v_mov_b64_e32 v[62:63], 0
	v_mov_b64_e32 v[64:65], 0
	v_mov_b64_e32 v[66:67], 0
	v_mov_b64_e32 v[68:69], 0
	v_mov_b64_e32 v[70:71], 0
	v_mov_b64_e32 v[72:73], 0
	v_mov_b64_e32 v[74:75], 0
	v_mov_b64_e32 v[76:77], 0
	v_mov_b64_e32 v[78:79], 0
	v_mov_b64_e32 v[80:81], 0
	v_mov_b64_e32 v[82:83], 0
	v_mov_b64_e32 v[84:85], 0
	v_mov_b64_e32 v[86:87], 0
	v_mov_b64_e32 v[88:89], 0
	v_mov_b64_e32 v[90:91], 0
	v_mov_b64_e32 v[92:93], 0
	v_mov_b64_e32 v[94:95], 0
	v_mov_b64_e32 v[96:97], 0
	v_mov_b64_e32 v[98:99], 0
	v_mov_b64_e32 v[100:101], 0
	v_mov_b64_e32 v[102:103], 0
	v_mov_b64_e32 v[104:105], 0
	v_mov_b64_e32 v[106:107], 0
	v_mov_b64_e32 v[108:109], 0
	v_mov_b64_e32 v[110:111], 0
	v_mov_b64_e32 v[112:113], 0
	v_mov_b64_e32 v[114:115], 0
	v_mov_b64_e32 v[116:117], 0
	v_mov_b64_e32 v[118:119], 0
	v_mov_b64_e32 v[120:121], 0
	v_mov_b64_e32 v[122:123], 0
	v_mov_b64_e32 v[124:125], 0
	v_mov_b64_e32 v[126:127], 0

.LBB0_1948:
	s_ashr_i32 s21, s20, 31
	s_lshl_b64 s[22:23], s[20:21], 19
	s_add_u32 s22, s0, s22
	s_addc_u32 s23, s1, s23
	s_and_b64 s[24:25], s[8:9], exec
	s_cselect_b32 s21, s23, s29
	s_cselect_b32 s45, s22, s28
	s_ashr_i32 s19, s18, 31
	s_lshl_b64 s[24:25], s[18:19], 19
	s_add_u32 s24, s4, s24
	s_addc_u32 s25, s5, s25
	s_and_b64 s[30:31], s[8:9], exec
	s_cselect_b32 s19, s25, s27
	s_cselect_b32 s46, s24, s26
	s_add_u32 s47, s26, 0x100
	s_addc_u32 s48, s27, 0
	s_add_u32 s26, s28, 0x40080
	s_addc_u32 s27, s29, 0
	s_mov_b32 s49, -2
	v_mov_b64_e32 v[0:1], 0
	v_mov_b64_e32 v[2:3], 0
	v_mov_b64_e32 v[4:5], 0
	v_mov_b64_e32 v[6:7], 0
	v_mov_b64_e32 v[8:9], 0
	v_mov_b64_e32 v[10:11], 0
	v_mov_b64_e32 v[12:13], 0
	v_mov_b64_e32 v[14:15], 0
	v_mov_b64_e32 v[16:17], 0
	v_mov_b64_e32 v[18:19], 0
	v_mov_b64_e32 v[20:21], 0
	v_mov_b64_e32 v[22:23], 0
	v_mov_b64_e32 v[24:25], 0
	v_mov_b64_e32 v[26:27], 0
	v_mov_b64_e32 v[28:29], 0
	v_mov_b64_e32 v[30:31], 0
	v_mov_b64_e32 v[32:33], 0
	v_mov_b64_e32 v[34:35], 0
	v_mov_b64_e32 v[36:37], 0
	v_mov_b64_e32 v[38:39], 0
	v_mov_b64_e32 v[40:41], 0
	v_mov_b64_e32 v[42:43], 0
	v_mov_b64_e32 v[44:45], 0
	v_mov_b64_e32 v[46:47], 0
	v_mov_b64_e32 v[48:49], 0
	v_mov_b64_e32 v[50:51], 0
	v_mov_b64_e32 v[52:53], 0
	v_mov_b64_e32 v[54:55], 0
	v_mov_b64_e32 v[56:57], 0
	v_mov_b64_e32 v[58:59], 0
	v_mov_b64_e32 v[60:61], 0
	v_mov_b64_e32 v[62:63], 0
	v_mov_b64_e32 v[64:65], 0
	v_mov_b64_e32 v[66:67], 0
	v_mov_b64_e32 v[68:69], 0
	v_mov_b64_e32 v[70:71], 0
	v_mov_b64_e32 v[72:73], 0
	v_mov_b64_e32 v[74:75], 0
	v_mov_b64_e32 v[76:77], 0
	v_mov_b64_e32 v[78:79], 0
	v_mov_b64_e32 v[80:81], 0
	v_mov_b64_e32 v[82:83], 0
	v_mov_b64_e32 v[84:85], 0
	v_mov_b64_e32 v[86:87], 0
	v_mov_b64_e32 v[88:89], 0
	v_mov_b64_e32 v[90:91], 0
	v_mov_b64_e32 v[92:93], 0
	v_mov_b64_e32 v[94:95], 0
	v_mov_b64_e32 v[96:97], 0
	v_mov_b64_e32 v[98:99], 0
	v_mov_b64_e32 v[100:101], 0
	v_mov_b64_e32 v[102:103], 0
	v_mov_b64_e32 v[104:105], 0
	v_mov_b64_e32 v[106:107], 0
	v_mov_b64_e32 v[108:109], 0
	v_mov_b64_e32 v[110:111], 0
	v_mov_b64_e32 v[112:113], 0
	v_mov_b64_e32 v[114:115], 0
	v_mov_b64_e32 v[116:117], 0
	v_mov_b64_e32 v[118:119], 0
	v_mov_b64_e32 v[120:121], 0
	v_mov_b64_e32 v[122:123], 0
	v_mov_b64_e32 v[124:125], 0
	v_mov_b64_e32 v[126:127], 0

.LBB0_2020:
	s_add_u32 s55, s34, 0x100
	s_addc_u32 s56, s35, 0
	s_mov_b32 s57, -2
	v_mov_b64_e32 v[0:1], 0
	v_mov_b64_e32 v[2:3], 0
	v_mov_b64_e32 v[4:5], 0
	v_mov_b64_e32 v[6:7], 0
	v_mov_b64_e32 v[8:9], 0
	v_mov_b64_e32 v[10:11], 0
	v_mov_b64_e32 v[12:13], 0
	v_mov_b64_e32 v[14:15], 0
	v_mov_b64_e32 v[16:17], 0
	v_mov_b64_e32 v[18:19], 0
	v_mov_b64_e32 v[20:21], 0
	v_mov_b64_e32 v[22:23], 0
	v_mov_b64_e32 v[24:25], 0
	v_mov_b64_e32 v[26:27], 0
	v_mov_b64_e32 v[28:29], 0
	v_mov_b64_e32 v[30:31], 0
	v_mov_b64_e32 v[32:33], 0
	v_mov_b64_e32 v[34:35], 0
	v_mov_b64_e32 v[36:37], 0
	v_mov_b64_e32 v[38:39], 0
	v_mov_b64_e32 v[40:41], 0
	v_mov_b64_e32 v[42:43], 0
	v_mov_b64_e32 v[44:45], 0
	v_mov_b64_e32 v[46:47], 0
	v_mov_b64_e32 v[48:49], 0
	v_mov_b64_e32 v[50:51], 0
	v_mov_b64_e32 v[52:53], 0
	v_mov_b64_e32 v[54:55], 0
	v_mov_b64_e32 v[56:57], 0
	v_mov_b64_e32 v[58:59], 0
	v_mov_b64_e32 v[60:61], 0
	v_mov_b64_e32 v[62:63], 0
	v_mov_b64_e32 v[64:65], 0
	v_mov_b64_e32 v[66:67], 0
	v_mov_b64_e32 v[68:69], 0
	v_mov_b64_e32 v[70:71], 0
	v_mov_b64_e32 v[72:73], 0
	v_mov_b64_e32 v[74:75], 0
	v_mov_b64_e32 v[76:77], 0
	v_mov_b64_e32 v[78:79], 0
	v_mov_b64_e32 v[80:81], 0
	v_mov_b64_e32 v[82:83], 0
	v_mov_b64_e32 v[84:85], 0
	v_mov_b64_e32 v[86:87], 0
	v_mov_b64_e32 v[88:89], 0
	v_mov_b64_e32 v[90:91], 0
	v_mov_b64_e32 v[92:93], 0
	v_mov_b64_e32 v[94:95], 0
	v_mov_b64_e32 v[96:97], 0
	v_mov_b64_e32 v[98:99], 0
	v_mov_b64_e32 v[100:101], 0
	v_mov_b64_e32 v[102:103], 0
	v_mov_b64_e32 v[104:105], 0
	v_mov_b64_e32 v[106:107], 0
	v_mov_b64_e32 v[108:109], 0
	v_mov_b64_e32 v[110:111], 0
	v_mov_b64_e32 v[112:113], 0
	v_mov_b64_e32 v[114:115], 0
	v_mov_b64_e32 v[116:117], 0
	v_mov_b64_e32 v[118:119], 0
	v_mov_b64_e32 v[120:121], 0
	v_mov_b64_e32 v[122:123], 0
	v_mov_b64_e32 v[124:125], 0
	v_mov_b64_e32 v[126:127], 0
